# instruction selection in the stick-breaking softplus: 32 redundant canonicalising v_max folded into the following max(0,x)
# speedup vs baseline: 1.0113x; 1.0017x over previous
; #define MFMA(a, b, c) __builtin_amdgcn_mfma_f32_32x32x16_bf16((a), (b), (c), 0, 0, 0)
; DI float fexp2(float x) { return __builtin_amdgcn_exp2f(x); }
; DI float flog2(float x) { return __builtin_amdgcn_logf(x); }
; DI f32x16 zero16() { f32x16 z; for (int i = 0; i < 16; ++i) z[i] = 0.f; return z; }
; DI void sb_item(const Params& P, int b, int hd, int qt, char* lds) {
;     ...
;         if (!done && kt * 64 < q0 + 31) {
;             f32x16 Z[2];
; #pragma unroll
;             for (int kb = 0; kb < 2; ++kb) {
;                 Z[kb] = zero16();
; #pragma unroll
;                 for (int ks = 0; ks < 4; ++ks) {
;                     const bf16x8 kf = *(const bf16x8*)(st + (32 * kb + l31) * 128 + (((2 * ks + h) ^ f) << 4));
;                     Z[kb] = MFMA(kf, qf[ks], Z[kb]);
;                 }
;             }
;             const bool diag = kt * 64 + 63 >= q0;
;             float run = R;
; #pragma unroll
;     ...
;                 float Lv[16];
;                 if (diag) {
; #pragma unroll
;                     for (int i = 0; i < 16; ++i) {
;                         const float z = Z[kb][i];
;                         const float sp = fmaxf(z, 0.f) + flog2(1.f + fexp2(-fabsf(z)));
;                         const int key = kt * 64 + 32 * kb + (i & 3) + 8 * (i >> 2) + 4 * h;
;                         const bool past = key < qpos;
;                         Lv[i] = past ? -sp : 0.f;
;                         Z[kb][i] = past ? z : -1e30f;
;                     }
;                 } else {
; #pragma unroll
;                     for (int i = 0; i < 16; ++i) {
;                         const float z = Z[kb][i];
;                         Lv[i] = -(fmaxf(z, 0.f) + flog2(1.f + fexp2(-fabsf(z))));
;                     }
.LBB0_150:
	s_and_b32 s17, s29, 1
	s_lshl_b32 s30, s17, 14
	s_xor_b64 s[8:9], s[10:11], -1
	s_mov_b64 s[10:11], -1
	s_and_saveexec_b64 s[22:23], s[8:9]
	s_cbranch_execz .LBB0_162
	s_add_i32 s31, s16, 64
	v_cmp_lt_i32_e64 s[8:9], s31, v97
	s_mov_b64 s[10:11], 0
	s_and_saveexec_b64 s[24:25], s[8:9]
	s_cbranch_execz .LBB0_161
	v_add_u32_e32 v0, s30, v99
	v_add_u32_e32 v169, v0, v101
	ds_read_b128 v[34:37], v169
	ds_read_b128 v[38:41], v169 offset:4096
	v_add_u32_e32 v168, v0, v103
	ds_read_b128 v[110:113], v168 offset:4096
	ds_read_b128 v[114:117], v168
	s_waitcnt lgkmcnt(0)
	v_mfma_f32_32x32x16_bf16 v[50:65], v[34:37], v[66:69], 0
	v_add_u32_e32 v167, v0, v105
	v_add_u32_e32 v0, v0, v107
	s_add_i32 s8, s16, 0x7f
	v_add_u32_e32 v171, s16, v95
	v_cmp_ge_i32_e64 s[8:9], s8, v93
	v_add_u32_e32 v170, 64, v171
	ds_read_b128 v[118:121], v167
	v_mfma_f32_32x32x16_bf16 v[34:49], v[38:41], v[66:69], 0
	ds_read_b128 v[122:125], v0
	v_mfma_f32_32x32x16_bf16 v[34:49], v[110:113], v[70:73], v[34:49]
	ds_read_b128 v[110:113], v167 offset:4096
	s_waitcnt lgkmcnt(0)
	v_mfma_f32_32x32x16_bf16 v[34:49], v[110:113], v[74:77], v[34:49]
	ds_read_b128 v[110:113], v0 offset:4096
	v_mfma_f32_32x32x16_bf16 v[50:65], v[114:117], v[70:73], v[50:65]
	s_waitcnt lgkmcnt(0)
	v_mfma_f32_32x32x16_bf16 v[34:49], v[110:113], v[78:81], v[34:49]
	v_mfma_f32_32x32x16_bf16 v[50:65], v[118:121], v[74:77], v[50:65]
	s_nop 10
	v_exp_f32_e64 v110, -|v34|
	v_max_f32_e32 v108, 0, v34
	v_exp_f32_e64 v113, -|v35|
	v_add_f32_e32 v110, 1.0, v110
	v_log_f32_e32 v110, v110
	v_exp_f32_e64 v127, -|v36|
	v_mfma_f32_32x32x16_bf16 v[50:65], v[122:125], v[78:81], v[50:65]
	v_exp_f32_e64 v129, -|v37|
	v_exp_f32_e64 v131, -|v38|
	v_exp_f32_e64 v133, -|v39|
	v_exp_f32_e64 v135, -|v40|
	v_exp_f32_e64 v142, -|v41|
	v_exp_f32_e64 v144, -|v42|
	v_exp_f32_e64 v146, -|v43|
	v_exp_f32_e64 v157, -|v44|
	v_exp_f32_e64 v159, -|v45|
	v_exp_f32_e64 v114, -|v46|
	v_add_f32_e32 v155, v108, v110
	v_exp_f32_e64 v108, -|v47|
	v_exp_f32_e64 v117, -|v48|
	v_exp_f32_e64 v119, -|v49|
	v_xor_b32_e32 v111, 0x80000000, v155
	v_max_f32_e32 v153, 0, v35
	v_add_f32_e32 v154, 1.0, v113
	v_max_f32_e32 v141, 0, v36
	v_add_f32_e32 v151, 1.0, v127
	v_max_f32_e32 v140, 0, v37
	v_add_f32_e32 v152, 1.0, v129
	v_max_f32_e32 v138, 0, v38
	v_add_f32_e32 v150, 1.0, v131
	v_max_f32_e32 v136, 0, v39
	v_add_f32_e32 v147, 1.0, v133
	v_max_f32_e32 v139, 0, v40
	v_add_f32_e32 v148, 1.0, v135
	v_max_f32_e32 v137, 0, v41
	v_add_f32_e32 v149, 1.0, v142
	v_max_f32_e32 v134, 0, v42
	v_add_f32_e32 v144, 1.0, v144
	v_max_f32_e32 v132, 0, v43
	v_add_f32_e32 v143, 1.0, v146
	v_max_f32_e32 v135, 0, v44
	v_add_f32_e32 v145, 1.0, v157
	v_max_f32_e32 v133, 0, v45
	v_add_f32_e32 v146, 1.0, v159
	v_max_f32_e32 v130, 0, v46
	v_add_f32_e32 v110, 1.0, v114
	v_max_f32_e32 v128, 0, v47
	v_add_f32_e32 v108, 1.0, v108
	v_max_f32_e32 v129, 0, v48
	v_add_f32_e32 v112, 1.0, v117
	v_max_f32_e32 v131, 0, v49
	v_add_f32_e32 v142, 1.0, v119
	s_and_saveexec_b64 s[10:11], s[8:9]
	s_xor_b64 s[26:27], exec, s[10:11]
	s_cbranch_execz .LBB0_154
	v_log_f32_e32 v113, v154
	v_log_f32_e32 v115, v151
	v_log_f32_e32 v114, v152
	v_add_u32_e32 v111, 0x60, v171
	v_cmp_lt_i32_e64 s[10:11], v111, v82
	v_add_u32_e32 v116, 0x61, v171
	v_add_f32_e32 v113, v153, v113
	v_cndmask_b32_e64 v111, 0, -v155, s[10:11]
	v_cndmask_b32_e64 v34, v178, v34, s[10:11]
	v_cmp_lt_i32_e64 s[10:11], v116, v82
	v_or_b32_e32 v116, 34, v170
	v_pk_add_f32 v[114:115], v[140:141], v[114:115]
	v_cndmask_b32_e64 v113, 0, -v113, s[10:11]
	v_cndmask_b32_e64 v35, v178, v35, s[10:11]
	v_or_b32_e32 v118, 35, v170
	v_cmp_lt_i32_e64 s[10:11], v116, v83
	v_log_f32_e32 v119, v149
	v_or_b32_e32 v122, 42, v170
	v_cndmask_b32_e64 v36, v178, v36, s[10:11]
	v_cndmask_b32_e64 v117, 0, -v115, s[10:11]
	v_cmp_lt_i32_e64 s[10:11], v118, v82
	v_log_f32_e32 v115, v148
	v_log_f32_e32 v118, v147
	v_cndmask_b32_e64 v116, 0, -v114, s[10:11]
	v_log_f32_e32 v114, v150
	v_or_b32_e32 v120, s31, v96
	v_cndmask_b32_e64 v37, v178, v37, s[10:11]
	v_cmp_lt_i32_e64 s[10:11], v120, v82
	v_pk_add_f32 v[114:115], v[138:139], v[114:115]
	v_pk_add_f32 v[120:121], v[136:137], v[118:119]
	v_or_b32_e32 v118, 41, v170
	v_cmp_lt_i32_e64 s[14:15], v122, v83
	v_cmp_lt_i32_e64 s[12:13], v118, v82
	v_cndmask_b32_e64 v118, 0, -v114, s[10:11]
	v_cndmask_b32_e64 v119, 0, -v115, s[14:15]
	v_log_f32_e32 v114, v144
	v_log_f32_e32 v115, v145
	v_mov_b32_e32 v138, s31
	v_or_b32_e32 v123, 43, v170
	v_cndmask_b32_e64 v38, v178, v38, s[10:11]
	v_cmp_lt_i32_e64 s[10:11], v123, v83
	v_log_f32_e32 v122, v143
	v_log_f32_e32 v123, v146
	v_or_b32_e32 v125, v138, v98
	v_cndmask_b32_e64 v121, 0, -v121, s[10:11]
	v_cndmask_b32_e64 v41, v178, v41, s[10:11]
	v_pk_add_f32 v[114:115], v[134:135], v[114:115]
	v_or_b32_e32 v124, 50, v170
	v_cmp_lt_i32_e64 s[10:11], v125, v82
	v_or_b32_e32 v125, 51, v170
	v_or_b32_e32 v126, 49, v170
	v_cndmask_b32_e64 v39, v178, v39, s[12:13]
	v_cndmask_b32_e64 v40, v178, v40, s[14:15]
	v_cndmask_b32_e64 v120, 0, -v120, s[12:13]
	v_cndmask_b32_e64 v42, v178, v42, s[10:11]
	v_cmp_lt_i32_e64 s[12:13], v126, v82
	v_cmp_lt_i32_e64 s[14:15], v124, v83
	v_cndmask_b32_e64 v114, 0, -v114, s[10:11]
	v_cmp_lt_i32_e64 s[10:11], v125, v83
	v_log_f32_e32 v124, v110
	v_log_f32_e32 v125, v142
	v_log_f32_e32 v126, v108
	v_log_f32_e32 v127, v112
	v_pk_add_f32 v[122:123], v[132:133], v[122:123]
	v_or_b32_e32 v110, v138, v100
	v_cndmask_b32_e64 v123, 0, -v123, s[10:11]
	v_cndmask_b32_e64 v45, v178, v45, s[10:11]
	v_cmp_lt_i32_e64 s[10:11], v110, v82
	v_or_b32_e32 v110, 58, v170
	v_cndmask_b32_e64 v43, v178, v43, s[12:13]
	v_cndmask_b32_e64 v122, 0, -v122, s[12:13]
	v_pk_add_f32 v[130:131], v[130:131], v[124:125]
	v_or_b32_e32 v108, 59, v170
	v_pk_add_f32 v[124:125], v[128:129], v[126:127]
	v_or_b32_e32 v112, 57, v170
	v_cmp_lt_i32_e64 s[12:13], v110, v83
	v_cndmask_b32_e64 v115, 0, -v115, s[14:15]
	v_cndmask_b32_e64 v44, v178, v44, s[14:15]
	v_cndmask_b32_e64 v125, 0, -v125, s[12:13]
	v_cmp_lt_i32_e64 s[14:15], v112, v82
	v_cndmask_b32_e64 v48, v178, v48, s[12:13]
	v_cmp_lt_i32_e64 s[12:13], v108, v83
	v_cndmask_b32_e64 v46, v178, v46, s[10:11]
	v_cndmask_b32_e64 v124, 0, -v124, s[14:15]
	v_cndmask_b32_e64 v47, v178, v47, s[14:15]
	v_cndmask_b32_e64 v127, 0, -v131, s[12:13]
	v_cndmask_b32_e64 v126, 0, -v130, s[10:11]
	v_cndmask_b32_e64 v49, v178, v49, s[12:13]

; DI float fexp2(float x) { return __builtin_amdgcn_exp2f(x); }
; DI float flog2(float x) { return __builtin_amdgcn_logf(x); }
; DI void sb_item(const Params& P, int b, int hd, int qt, char* lds) {
;     ...
; #pragma unroll
;     ...
;                 float Lv[16];
;                 if (diag) {
; #pragma unroll
;                     for (int i = 0; i < 16; ++i) {
;                         const float z = Z[kb][i];
;                         const float sp = fmaxf(z, 0.f) + flog2(1.f + fexp2(-fabsf(z)));
;                         const int key = kt * 64 + 32 * kb + (i & 3) + 8 * (i >> 2) + 4 * h;
;                         const bool past = key < qpos;
;                         Lv[i] = past ? -sp : 0.f;
;                         Z[kb][i] = past ? z : -1e30f;
;                     }
;                 } else {
; #pragma unroll
;                     for (int i = 0; i < 16; ++i) {
;                         const float z = Z[kb][i];
;                         Lv[i] = -(fmaxf(z, 0.f) + flog2(1.f + fexp2(-fabsf(z))));
;                     }
;                 }
;                 float cs[4], ps[4];
; #pragma unroll
;                 for (int g = 0; g < 4; ++g) { cs[g] = (Lv[4 * g] + Lv[4 * g + 1]) + (Lv[4 * g + 2] + Lv[4 * g + 3]); ps[g] = __shfl_xor(cs[g], 32); }
.LBB0_156:
	s_or_b64 exec, exec, s[10:11]
	v_pk_add_f32 v[128:129], v[124:125], v[126:127]
	v_pk_add_f32 v[132:133], v[122:123], v[114:115]
	v_pk_add_f32 v[128:129], v[128:129], v[128:129] op_sel:[0,1] op_sel_hi:[1,0]
	ds_bpermute_b32 v131, v166, v128
	v_pk_mov_b32 v[128:129], v[132:133], v[128:129] op_sel:[1,0]
	v_exp_f32_e64 v130, -|v50|
	v_mov_b32_e32 v112, v116
	v_mov_b32_e32 v110, v117
	s_waitcnt lgkmcnt(0)
	v_mov_b32_e32 v133, v131
	v_pk_add_f32 v[128:129], v[128:129], v[132:133]
	ds_bpermute_b32 v108, v166, v128
	v_pk_add_f32 v[132:133], v[120:121], v[118:119]
	v_pk_add_f32 v[134:135], v[112:113], v[110:111]
	v_exp_f32_e64 v139, -|v53|
	v_add_f32_e32 v110, v134, v135
	s_waitcnt lgkmcnt(0)
	v_pk_add_f32 v[136:137], v[128:129], v[108:109]
	ds_bpermute_b32 v112, v166, v110
	v_pk_mov_b32 v[128:129], v[132:133], v[136:137] op_sel:[1,0]
	v_mov_b32_e32 v133, v137
	v_pk_add_f32 v[134:135], v[128:129], v[132:133]
	v_add_f32_e32 v128, 1.0, v130
	v_log_f32_e32 v128, v128
	ds_bpermute_b32 v129, v166, v134
	v_exp_f32_e64 v132, -|v51|
	v_exp_f32_e64 v136, -|v52|
	v_exp_f32_e64 v141, -|v54|
	v_exp_f32_e64 v143, -|v55|
	v_exp_f32_e64 v145, -|v56|
	v_exp_f32_e64 v147, -|v57|
	v_exp_f32_e64 v149, -|v58|
	v_exp_f32_e64 v151, -|v59|
	v_exp_f32_e64 v153, -|v60|
	v_exp_f32_e64 v172, -|v61|
	v_exp_f32_e64 v184, -|v62|
	v_exp_f32_e64 v186, -|v63|
	v_exp_f32_e64 v201, -|v64|
	v_exp_f32_e64 v203, -|v65|
	v_max_f32_e32 v130, 0, v50
	v_add_f32_e32 v199, v130, v128
	v_xor_b32_e32 v128, 0x80000000, v199
	v_max_f32_e32 v197, 0, v51
	v_add_f32_e32 v198, 1.0, v132
	v_max_f32_e32 v164, 0, v52
	v_add_f32_e32 v195, 1.0, v136
	v_max_f32_e32 v165, 0, v53
	v_add_f32_e32 v196, 1.0, v139
	v_max_f32_e32 v160, 0, v54
	v_add_f32_e32 v194, 1.0, v141
	v_max_f32_e32 v158, 0, v55
	v_add_f32_e32 v191, 1.0, v143
	v_max_f32_e32 v161, 0, v56
	v_add_f32_e32 v192, 1.0, v145
	v_max_f32_e32 v159, 0, v57
	v_add_f32_e32 v193, 1.0, v147
	v_max_f32_e32 v156, 0, v58
	v_add_f32_e32 v188, 1.0, v149
	v_max_f32_e32 v154, 0, v59
	v_add_f32_e32 v187, 1.0, v151
	v_max_f32_e32 v157, 0, v60
	v_add_f32_e32 v189, 1.0, v153
	v_max_f32_e32 v155, 0, v61
	v_add_f32_e32 v190, 1.0, v172
	v_max_f32_e32 v148, 0, v62
	v_add_f32_e32 v184, 1.0, v184
	v_max_f32_e32 v146, 0, v63
	v_add_f32_e32 v136, 1.0, v186
	v_max_f32_e32 v147, 0, v64
	v_add_f32_e32 v185, 1.0, v201
	v_max_f32_e32 v149, 0, v65
	v_add_f32_e32 v186, 1.0, v203
	s_and_saveexec_b64 s[10:11], s[8:9]
	s_xor_b64 s[14:15], exec, s[10:11]
	s_cbranch_execz .LBB0_158
	v_log_f32_e32 v130, v198
	v_cmp_lt_i32_e64 s[8:9], v170, v82
	v_add_u32_e32 v138, 0x41, v171
	v_log_f32_e32 v132, v195
	v_cndmask_b32_e64 v128, 0, -v199, s[8:9]
	v_cndmask_b32_e64 v50, v178, v50, s[8:9]
	v_add_f32_e32 v130, v197, v130
	v_log_f32_e32 v133, v196
	v_cmp_lt_i32_e64 s[8:9], v138, v82
	v_or_b32_e32 v138, 3, v170
	v_or_b32_e32 v139, 2, v170
	v_cndmask_b32_e64 v130, 0, -v130, s[8:9]
	v_cndmask_b32_e64 v51, v178, v51, s[8:9]
	v_cmp_lt_i32_e64 s[8:9], v138, v83
	v_cmp_lt_i32_e64 s[10:11], v139, v82
	v_log_f32_e32 v138, v194
	v_log_f32_e32 v139, v192
	v_pk_add_f32 v[132:133], v[164:165], v[132:133]
	v_or_b32_e32 v142, 10, v170
	v_or_b32_e32 v143, s31, v102
	v_cndmask_b32_e64 v133, 0, -v133, s[8:9]
	v_cndmask_b32_e64 v53, v178, v53, s[8:9]
	v_log_f32_e32 v140, v191
	v_log_f32_e32 v141, v193
	v_pk_add_f32 v[138:139], v[160:161], v[138:139]
	v_cmp_lt_i32_e64 s[8:9], v143, v82
	v_or_b32_e32 v143, 9, v170
	v_cmp_lt_i32_e64 s[12:13], v142, v83
	v_cndmask_b32_e64 v132, 0, -v132, s[10:11]
	v_cndmask_b32_e64 v52, v178, v52, s[10:11]
	v_cmp_lt_i32_e64 s[10:11], v143, v82
	v_cndmask_b32_e64 v143, 0, -v139, s[12:13]
	v_cndmask_b32_e64 v142, 0, -v138, s[8:9]
	v_log_f32_e32 v138, v188
	v_log_f32_e32 v139, v189
	v_mov_b32_e32 v160, s31
	v_or_b32_e32 v144, 11, v170
	v_cndmask_b32_e64 v54, v178, v54, s[8:9]
	v_pk_add_f32 v[140:141], v[158:159], v[140:141]
	v_cmp_lt_i32_e64 s[8:9], v144, v83
	v_or_b32_e32 v151, v160, v104
	v_pk_add_f32 v[138:139], v[156:157], v[138:139]
	v_cndmask_b32_e64 v145, 0, -v141, s[8:9]
	v_cndmask_b32_e64 v57, v178, v57, s[8:9]
	v_or_b32_e32 v150, 18, v170
	v_cmp_lt_i32_e64 s[8:9], v151, v82
	v_or_b32_e32 v151, 19, v170
	v_cndmask_b32_e64 v56, v178, v56, s[12:13]
	v_cndmask_b32_e64 v144, 0, -v140, s[10:11]
	v_log_f32_e32 v140, v187
	v_log_f32_e32 v141, v190
	v_cndmask_b32_e64 v58, v178, v58, s[8:9]
	v_cmp_lt_i32_e64 s[12:13], v150, v83
	v_cndmask_b32_e64 v138, 0, -v138, s[8:9]
	v_cmp_lt_i32_e64 s[8:9], v151, v83
	v_log_f32_e32 v150, v184
	v_log_f32_e32 v151, v186
	v_or_b32_e32 v152, 17, v170
	v_cndmask_b32_e64 v55, v178, v55, s[10:11]
	v_cmp_lt_i32_e64 s[10:11], v152, v82
	v_log_f32_e32 v152, v136
	v_log_f32_e32 v153, v185
	v_pk_add_f32 v[140:141], v[154:155], v[140:141]
	v_pk_add_f32 v[148:149], v[148:149], v[150:151]
	v_or_b32_e32 v150, v160, v106
	v_cndmask_b32_e64 v141, 0, -v141, s[8:9]
	v_cndmask_b32_e64 v61, v178, v61, s[8:9]
	v_cmp_lt_i32_e64 s[8:9], v150, v82
	v_or_b32_e32 v150, 26, v170
	v_cndmask_b32_e64 v59, v178, v59, s[10:11]
	v_cndmask_b32_e64 v140, 0, -v140, s[10:11]
	v_or_b32_e32 v136, 27, v170
	v_pk_add_f32 v[146:147], v[146:147], v[152:153]
	v_or_b32_e32 v152, 25, v170
	v_cmp_lt_i32_e64 s[10:11], v150, v83
	v_cndmask_b32_e64 v139, 0, -v139, s[12:13]
	v_cndmask_b32_e64 v60, v178, v60, s[12:13]
	v_cndmask_b32_e64 v151, 0, -v147, s[10:11]
	v_cmp_lt_i32_e64 s[12:13], v152, v82
	v_cndmask_b32_e64 v64, v178, v64, s[10:11]
	v_cmp_lt_i32_e64 s[10:11], v136, v83
	v_cndmask_b32_e64 v62, v178, v62, s[8:9]
	v_cndmask_b32_e64 v150, 0, -v146, s[12:13]
	v_cndmask_b32_e64 v63, v178, v63, s[12:13]
	v_cndmask_b32_e64 v153, 0, -v149, s[10:11]
	v_cndmask_b32_e64 v152, 0, -v148, s[8:9]
	v_cndmask_b32_e64 v65, v178, v65, s[10:11]
